# MLA dense loop: K/V staging via LDS-DMA (padded linear image) issued after the S-phase MFMAs + MLA row-sum moved to matrix pipe (selector MFMA); rest as p26
# speedup vs baseline: 1.0300x; 1.0170x over previous
; template <int DQK, bool BAND, int QT> ...
;     ...
;   const int tid = tid_(), lane = tid & 63, w = tid >> 6, h = lane >> 5, ql = lane & 31;
;   float* bias_l = (float*)(lds + 2 * ST);
;   if (BAND) { if (tid < 129) bias_l[tid] = bias_g[tid]; }
;   bf16x8 qf[QT][NKS];
; #pragma unroll
;   for (int qt = 0; qt < QT; ++qt)
; #pragma unroll
;     for (int ks = 0; ks < NKS; ++ks) qf[qt][ks] = *(const bf16x8*)(Q + (size_t)(w * WQ + qt * 32 + ql) * DQK + ks * 16 + h * 8);
;   f32x16 o[2][QT];
; #pragma unroll
;   for (int a = 0; a < 2; ++a)
; #pragma unroll
;     for (int b = 0; b < QT; ++b)
; #pragma unroll
;       for (int r = 0; r < 16; ++r) o[a][b][r] = 0.f;
;   float m[QT], l[QT];
; #pragma unroll
;   for (int qt = 0; qt < QT; ++qt) { m[qt] = -1e30f; l[qt] = 0.f; }
;   u32x4 rk[NKL], rv[2];
;   const int vrow0 = tid >> 3, vch = tid & 7;
;   unsigned klds[NKL];
; #pragma unroll
;   for (int i = 0; i < NKL; ++i) { const int idx = tid + i * 256, kr = idx / KV4, kc = idx - kr * KV4; klds[i] = kr * KROW + kc * 16; }
;   const unsigned koff0 = (unsigned)tid * 16u;
;   const unsigned voff0 = (unsigned)(vrow0 * ldv + vch * 8) * 2u, vstep = (unsigned)(32 * ldv) * 2u;
;   const unsigned vlds0 = KST + vrow0 * LROW + vch * 16;
;   auto gload = [&](int kt) {
;     const char* kb = (const char*)Kp + (size_t)kt * (DQK * 2);
;     const char* vb = (const char*)Vt + (size_t)kt * 2;
; #pragma unroll
;     for (int i = 0; i < NKL; ++i) rk[i] = *(const u32x4*)(kb + (koff0 + i * 4096u));
; #pragma unroll
; DI void phase_attn(const Ctx& c) {
;     ...
;     if (item < n_mla) {
;       const int hh = item & 7, rest = item >> 3, seq = rest / nqb, qb = rest - seq * nqb;
;       const size_t hs = (size_t)(seq * 8 + hh) * S;
;       if (ATT_PIPE) attn_dense<96>(wsb(c, OFF_QA) + (hs + qb * QBLK) * 96, wsb(c, OFF_KA) + hs * 96, wsb(c, OFF_VTA) + (size_t)(seq * 8 + hh) * 64 * (S + 64), S + 64,
;                      S, 0.10206207261596577f * LOG2E, wsb(c, OFF_OA) + ((size_t)seq * S + qb * QBLK) * LDO + hh * 64, LDO, c.lds);
;       else attn_item<96, false, AQT>(wsb(c, OFF_QA) + (hs + qb * QBLK) * 96, wsb(c, OFF_KA) + hs * 96, wsb(c, OFF_VTA) + (size_t)(seq * 8 + hh) * 64 * (S + 64), S + 64,
;                      0, S, 0, nullptr, 0.10206207261596577f * LOG2E, wsb(c, OFF_OA) + ((size_t)seq * S + qb * QBLK) * LDO + hh * 64, LDO, nullptr, 0, c.lds);
.LBB0_839:
	s_andn2_b64 vcc, exec, s[0:1]
	s_cbranch_vccnz .LBB0_664
	s_abs_i32 s0, s25
	v_readlane_b32 s1, v248, 3
	s_mul_hi_u32 s1, s0, s1
	v_readlane_b32 s4, v248, 2
	s_mul_i32 s2, s1, s4
	s_sub_i32 s0, s0, s2
	s_ashr_i32 s7, s25, 31
	s_add_i32 s2, s1, 1
	s_sub_i32 s3, s0, s4
	s_cmp_ge_u32 s0, s4
	s_cselect_b32 s1, s2, s1
	s_cselect_b32 s0, s3, s0
	s_add_i32 s2, s1, 1
	s_cmp_ge_u32 s0, s4
	s_cselect_b32 s0, s2, s1
	s_xor_b32 s38, s0, s7
	s_sub_i32 s0, s38, s7
	s_lshl_b32 s1, s0, s60
	s_lshl_b32 s2, s0, 3
	v_readlane_b32 s40, v249, 31
	s_sub_i32 s1, s25, s1
	s_or_b32 s26, s2, s40
	s_ashr_i32 s27, s26, 31
	s_lshl_b32 s4, s1, 8
	s_lshl_b64 s[34:35], s[26:27], s20
	s_ashr_i32 s5, s4, 31
	s_add_u32 s1, s34, s4
	s_addc_u32 s2, s35, s5
	s_mulk_i32 s2, 0xc0
	s_mul_hi_u32 s3, s1, 0xc0
	s_add_i32 s3, s3, s2
	s_mulk_i32 s1, 0xc0
	v_readlane_b32 s42, v250, 40
	v_readlane_b32 s43, v250, 41
	s_add_u32 s2, s42, s1
	s_mul_i32 s1, s35, 0xc0
	s_mul_hi_u32 s6, s34, 0xc0
	s_addc_u32 s3, s43, s3
	s_add_i32 s25, s6, s1
	s_mul_i32 s39, s34, 0xc0
	v_readlane_b32 s34, v250, 38
	v_readlane_b32 s35, v250, 39
	s_add_u32 s34, s34, s39
	v_mov_b32_e32 v2, v199
	s_addc_u32 s35, s35, s25
	v_readlane_b32 s1, v249, 61
	v_lshlrev_b32_e32 v4, 4, v2
	global_load_dwordx4 v[130:133], v4, s[34:35]
	v_add_u32_e32 v8, 0x1000, v4
	global_load_dwordx4 v[134:137], v8, s[34:35]
	s_mul_hi_i32 s27, s26, s1
	s_mul_i32 s26, s26, s1
	s_lshl_b64 s[26:27], s[26:27], 1
	v_readlane_b32 s42, v250, 36
	v_ashrrev_i32_e32 v3, 3, v2
	v_readlane_b32 s6, v249, 63
	v_readlane_b32 s43, v250, 37
	s_add_u32 s26, s42, s26
	v_and_b32_e32 v6, 0x70, v4
	v_mul_lo_u32 v0, v3, s6
	s_addc_u32 s27, s43, s27
	v_add_u32_e32 v10, 0x2000, v4
	v_or_b32_e32 v12, v6, v0
	v_bfe_u32 v230, v2, 5, 1
	global_load_dwordx4 v[138:141], v10, s[34:35]
	v_add_u32_e32 v14, s1, v12
	global_load_dwordx4 v[146:149], v12, s[26:27]
	global_load_dwordx4 v[170:173], v14, s[26:27]
	v_lshlrev_b32_e32 v0, 4, v230
	v_and_b32_e32 v204, 0xffffffdf, v2
	v_lshl_add_u64 v[16:17], s[2:3], 0, v[0:1]
	s_movk_i32 s1, 0xc0
	v_or_b32_e32 v202, 32, v2
	v_mad_i64_i32 v[18:19], s[2:3], v204, s1, v[16:17]
	v_mad_i64_i32 v[16:17], s[2:3], v202, s1, v[16:17]
	global_load_dwordx4 v[142:145], v[18:19], off
	global_load_dwordx4 v[150:153], v[18:19], off offset:32
	global_load_dwordx4 v[154:157], v[18:19], off offset:64
	global_load_dwordx4 v[158:161], v[18:19], off offset:96
	global_load_dwordx4 v[162:165], v[18:19], off offset:128
	global_load_dwordx4 v[166:169], v[18:19], off offset:160
	global_load_dwordx4 v[174:177], v[16:17], off
	global_load_dwordx4 v[178:181], v[16:17], off offset:32
	global_load_dwordx4 v[182:185], v[16:17], off offset:64
	global_load_dwordx4 v[186:189], v[16:17], off offset:96
	global_load_dwordx4 v[190:193], v[16:17], off offset:128
	global_load_dwordx4 v[194:197], v[16:17], off offset:160
	s_mov_b32 s1, 0x2aaaaaab
	v_mul_hi_i32 v5, v2, s1
	v_lshrrev_b32_e32 v7, 31, v5
	v_ashrrev_i32_e32 v5, 1, v5
	v_add_u32_e32 v5, v5, v7
	s_movk_i32 s6, 0xd0
	v_mad_u64_u32 v[16:17], s[2:3], v5, -12, v[2:3]
	v_mul_lo_u32 v5, v5, s6
	v_lshl_add_u32 v231, v16, 4, v5
	v_add_u32_e32 v16, 0x100, v2
	v_mul_hi_i32 v5, v16, s1
	v_lshrrev_b32_e32 v7, 31, v5
	v_ashrrev_i32_e32 v5, 1, v5
	v_add_u32_e32 v5, v5, v7
	v_mad_u64_u32 v[16:17], s[2:3], v5, -12, v[16:17]
	v_mul_lo_u32 v5, v5, s6
	v_lshl_add_u32 v232, v16, 4, v5
	v_add_u32_e32 v16, 0x200, v2
	v_mul_hi_i32 v5, v16, s1
	v_lshrrev_b32_e32 v7, 31, v5
	v_ashrrev_i32_e32 v5, 1, v5
	v_add_u32_e32 v5, v5, v7
	v_mad_u64_u32 v[16:17], s[2:3], v5, -12, v[16:17]
	v_mul_lo_u32 v5, v5, s6
	v_add_u32_e32 v7, 0, v231
	v_lshl_add_u32 v233, v16, 4, v5
	v_mov_b32_e32 v13, v1
	v_mov_b32_e32 v15, v1
	v_cmp_lt_i32_e32 vcc, v221, v220
	v_mov_b32_e32 v5, v1
	v_mov_b32_e32 v9, v1
	v_mov_b32_e32 v11, v1
	v_mov_b32_e32 v50, v1
	v_mov_b32_e32 v51, v1
	v_mov_b32_e32 v52, v1
	v_mov_b32_e32 v53, v1
	v_mov_b32_e32 v54, v1
	v_mov_b32_e32 v55, v1
	v_mov_b32_e32 v56, v1
	v_mov_b32_e32 v57, v1
	v_mov_b32_e32 v58, v1
	v_mov_b32_e32 v59, v1
	v_mov_b32_e32 v60, v1
	v_mov_b32_e32 v61, v1
	v_mov_b32_e32 v62, v1
	v_mov_b32_e32 v63, v1
	s_waitcnt vmcnt(16)
	ds_write_b128 v7, v[130:133]
	v_add_u32_e32 v7, 0, v232
	s_waitcnt vmcnt(15)
	ds_write_b128 v7, v[134:137]
	v_add_u32_e32 v7, 0, v233
	v_mad_u64_u32 v[206:207], s[2:3], v3, s16, v[6:7]
	s_lshl_b32 s2, s38, 3
	s_or_b32 s2, s40, s2
	s_lshl_b32 s3, s7, 3
	v_add_u32_e32 v3, 0, v206
	s_sub_i32 s2, s2, s3
	v_readlane_b32 s7, v248, 4
	s_mul_hi_i32 s3, s7, s2
	s_mul_i32 s2, s7, s2
	v_lshlrev_b32_e32 v6, 1, v2
	s_add_u32 s2, s2, 0x10d35980
	v_and_b32_e32 v6, 8, v6
	s_waitcnt vmcnt(14)
	ds_write_b128 v7, v[138:141]
	s_waitcnt vmcnt(13)
	ds_write_b128 v3, v[146:149] offset:13312
	s_waitcnt vmcnt(12)
; template <int DQK, bool BAND, int QT> ...
;     ...
;   u32x4 rk[NKL], rv[2];
;   const int vrow0 = tid >> 3, vch = tid & 7;
;   unsigned klds[NKL];
; #pragma unroll
;   for (int i = 0; i < NKL; ++i) { const int idx = tid + i * 256, kr = idx / KV4, kc = idx - kr * KV4; klds[i] = kr * KROW + kc * 16; }
;   const unsigned koff0 = (unsigned)tid * 16u;
;   const unsigned voff0 = (unsigned)(vrow0 * ldv + vch * 8) * 2u, vstep = (unsigned)(32 * ldv) * 2u;
;   const unsigned vlds0 = KST + vrow0 * LROW + vch * 16;
;   auto gload = [&](int kt) {
;     const char* kb = (const char*)Kp + (size_t)kt * (DQK * 2);
;     const char* vb = (const char*)Vt + (size_t)kt * 2;
; #pragma unroll
;     for (int i = 0; i < NKL; ++i) rk[i] = *(const u32x4*)(kb + (koff0 + i * 4096u));
; #pragma unroll
;     for (int i = 0; i < 2; ++i) rv[i] = *(const u32x4*)(vb + (voff0 + i * vstep));
;   };
;   auto lstore = [&](char* st) {
; #pragma unroll
;     for (int i = 0; i < NKL; ++i) *(u32x4*)(st + klds[i]) = rk[i];
; #pragma unroll
;     for (int i = 0; i < 2; ++i) *(u32x4*)(st + vlds0 + i * 32 * LROW) = rv[i];
;   };
;   gload(kbeg);
;   lstore(lds);
;   __syncthreads();
;   const int pr = (ql & ~12) | ((ql & 4) << 1) | ((ql & 8) >> 1);
;   const int k_rd = pr * KROW + h * 16;
;   const int v_rd = KST + ql * LROW + h * 16;
;   const int qw0 = q0 + w * WQ;
	ds_write_b128 v3, v[170:173] offset:17920
	v_and_b32_e32 v3, 31, v2
	v_mul_u32_u24_e32 v234, 0x90, v3
	v_and_b32_e32 v3, 19, v2
	v_lshrrev_b32_e32 v2, 1, v2
	v_and_b32_e32 v2, 4, v2
	s_addc_u32 s3, s3, 0
	v_or3_b32 v2, v3, v6, v2
	v_lshl_add_u64 v[208:209], s[2:3], 0, v[12:13]
	v_lshl_add_u64 v[210:211], s[2:3], 0, v[14:15]
	s_add_u32 s2, s39, 0xf538900
	v_mul_u32_u24_e32 v235, 0xd0, v2
	v_cndmask_b32_e32 v2, v219, v221, vcc
	s_addc_u32 s3, s25, 0
	v_lshlrev_b32_e32 v203, 2, v2
	v_lshl_add_u64 v[212:213], s[2:3], 0, v[4:5]
	v_lshl_add_u64 v[214:215], s[2:3], 0, v[8:9]
	v_lshl_add_u64 v[216:217], s[2:3], 0, v[10:11]
	v_mov_b32_e32 v64, v1
	v_mov_b32_e32 v65, v1
	v_mov_b64_e32 v[18:19], v[50:51]
	v_mov_b64_e32 v[34:35], v[50:51]
	v_mov_b64_e32 v[2:3], v[50:51]
	s_mov_b32 s1, 0
	s_mov_b32 s6, 64
	v_mov_b32_e32 v237, 0xf149f2ca
	v_mov_b32_e32 v236, 0
	v_mov_b32_e32 v207, 0
	v_mov_b32_e32 v238, 0xf149f2ca
	v_mov_b64_e32 v[20:21], v[52:53]
	v_mov_b64_e32 v[22:23], v[54:55]
	v_mov_b64_e32 v[24:25], v[56:57]
	v_mov_b64_e32 v[26:27], v[58:59]
	v_mov_b64_e32 v[28:29], v[60:61]
	v_mov_b64_e32 v[30:31], v[62:63]
	v_mov_b64_e32 v[32:33], v[64:65]
	v_mov_b64_e32 v[36:37], v[52:53]
	v_mov_b64_e32 v[38:39], v[54:55]
	v_mov_b64_e32 v[40:41], v[56:57]
	v_mov_b64_e32 v[42:43], v[58:59]
	v_mov_b64_e32 v[44:45], v[60:61]
	v_mov_b64_e32 v[46:47], v[62:63]
	v_mov_b64_e32 v[48:49], v[64:65]
	v_mov_b64_e32 v[4:5], v[52:53]
	v_mov_b64_e32 v[6:7], v[54:55]
	v_mov_b64_e32 v[8:9], v[56:57]
	v_mov_b64_e32 v[10:11], v[58:59]
	v_mov_b64_e32 v[12:13], v[60:61]
	v_mov_b64_e32 v[14:15], v[62:63]
	v_mov_b64_e32 v[16:17], v[64:65]
	v_add_u32_e32 v235, v235, v0
	v_add_u32_e32 v234, v234, v0
	v_mbcnt_lo_u32_b32 v254, -1, 0
	v_mbcnt_hi_u32_b32 v254, -1, v254
	v_and_b32_e32 v255, 15, v254
	v_lshrrev_b32_e32 v253, 4, v254
	v_and_b32_e32 v253, 1, v253
	v_cmp_eq_u32_e32 vcc, v255, v253
	v_mov_b32_e32 v253, 0x3f803f80
	s_nop 1
	v_cndmask_b32_e32 v130, 0, v253, vcc
	v_mov_b32_e32 v131, v130
	v_mov_b32_e32 v132, v130
	v_mov_b32_e32 v133, v130
	v_mov_b32_e32 v134, 0
	v_mov_b32_e32 v135, 0
	v_mov_b32_e32 v136, 0
	v_mov_b32_e32 v137, 0
	v_mov_b32_e32 v138, 0
	v_mov_b32_e32 v139, 0
	v_mov_b32_e32 v140, 0
	v_mov_b32_e32 v141, 0
	v_readfirstlane_b32 s38, v199
	s_lshr_b32 s38, s38, 6
	s_lshl_b32 s39, s38, 10
	v_readlane_b32 s25, v249, 63
	v_mov_b32_e32 v253, v199
	v_mul_u32_u24_e32 v254, 0x13b2, v253
	v_lshrrev_b32_e32 v254, 16, v254
	v_mul_u32_u24_e32 v255, 13, v254
	v_sub_u32_e32 v255, v253, v255
	v_min_u32_e32 v255, 11, v255
	v_mul_u32_u24_e32 v254, 0xc0, v254
	v_lshl_add_u32 v146, v255, 4, v254
	v_add_u32_e32 v253, 0x100, v199
	v_mul_u32_u24_e32 v254, 0x13b2, v253
	v_lshrrev_b32_e32 v254, 16, v254
	v_mul_u32_u24_e32 v255, 13, v254
	v_sub_u32_e32 v255, v253, v255
	v_min_u32_e32 v255, 11, v255
	v_mul_u32_u24_e32 v254, 0xc0, v254
	v_lshl_add_u32 v147, v255, 4, v254
	v_add_u32_e32 v253, 0x200, v199
	v_mul_u32_u24_e32 v254, 0x13b2, v253
	v_lshrrev_b32_e32 v254, 16, v254
	v_mul_u32_u24_e32 v255, 13, v254
	v_sub_u32_e32 v255, v253, v255
	v_min_u32_e32 v255, 11, v255
	v_mul_u32_u24_e32 v254, 0xc0, v254
	v_lshl_add_u32 v148, v255, 4, v254
	v_mov_b32_e32 v253, v199
	v_mul_u32_u24_e32 v254, 0x1c72, v253
	v_lshrrev_b32_e32 v254, 16, v254
	v_mul_u32_u24_e32 v255, 9, v254
	v_sub_u32_e32 v255, v253, v255
	v_min_u32_e32 v255, 7, v255
	v_mul_lo_u32 v254, v254, s25
	v_lshl_add_u32 v170, v255, 4, v254
	v_add_u32_e32 v253, 0x100, v199
	v_mul_u32_u24_e32 v254, 0x1c72, v253
	v_lshrrev_b32_e32 v254, 16, v254
	v_mul_u32_u24_e32 v255, 9, v254
	v_sub_u32_e32 v255, v253, v255
	v_min_u32_e32 v255, 7, v255
	v_mul_lo_u32 v254, v254, s25
	v_lshl_add_u32 v171, v255, 4, v254
	v_add_u32_e32 v253, 0x300, v199
	v_mul_u32_u24_e32 v254, 0x13b2, v253
	v_lshrrev_b32_e32 v254, 16, v254
	v_mul_u32_u24_e32 v255, 13, v254
	v_sub_u32_e32 v255, v253, v255
	v_min_u32_e32 v255, 11, v255
	v_mul_u32_u24_e32 v254, 0xc0, v254
	v_lshl_add_u32 v149, v255, 4, v254
	v_add_u32_e32 v253, 0x1c0, v199
	v_mul_u32_u24_e32 v254, 0x1c72, v253
	v_lshrrev_b32_e32 v254, 16, v254
	v_mul_u32_u24_e32 v255, 9, v254
	v_sub_u32_e32 v255, v253, v255
	v_min_u32_e32 v255, 7, v255
	v_mul_lo_u32 v254, v254, s25
	v_lshl_add_u32 v172, v255, 4, v254
	v_cmp_gt_u32_e32 vcc, 64, v199
	s_nop 1
	v_cndmask_b32_e32 v149, v172, v149, vcc
	v_readfirstlane_b32 s34, v212
	v_readfirstlane_b32 s35, v213
	s_add_u32 s34, s34, s94
	s_addc_u32 s35, s35, s95
	s_sub_u32 s34, s34, s39
	s_subb_u32 s35, s35, 0
	v_readfirstlane_b32 s26, v208
	v_readfirstlane_b32 s27, v209
	s_add_u32 s26, s26, s94
	s_addc_u32 s27, s27, s95
	s_mul_i32 s42, s38, s25
	s_lshl_b32 s42, s42, 3
	s_sub_u32 s26, s26, s42
	s_subb_u32 s27, s27, 0
	s_waitcnt vmcnt(0) lgkmcnt(0)
	s_barrier
; #define MFMA(a, b, c) __builtin_amdgcn_mfma_f32_32x32x16_bf16((a), (b), (c), 0, 0, 0)
; template <int DQK, bool BAND, int QT> ...
;     ...
;   for (int kt = kbeg; kt < kend; kt += 64, ++it) {
;     const char* st = lds + (it & 1) * ST;
;     const bool more = (kt + 64 < kend);
;     if (more) gload(kt + 64);
;     bool need = true;
;     if (BAND) need = (kt + 63 >= qw0 - 64) && (kt <= qw0 + WQ - 1 + 64);
;     if (need) {
;       f32x16 s[2][QT];
; #pragma unroll
;       for (int a = 0; a < 2; ++a)
; #pragma unroll
;         for (int b = 0; b < QT; ++b)
; #pragma unroll
;           for (int r = 0; r < 16; ++r) s[a][b][r] = 0.f;
; #pragma unroll
;       for (int ks = 0; ks < NKS; ++ks) {
;         const bf16x8 k0 = *(const bf16x8*)(st + k_rd + ks * 32);
;         const bf16x8 k1 = *(const bf16x8*)(st + k_rd + 32 * KROW + ks * 32);
; #pragma unroll
;         for (int qt = 0; qt < QT; ++qt) {
;           s[0][qt] = MFMA(k0, qf[qt][ks], s[0][qt]);
;           s[1][qt] = MFMA(k1, qf[qt][ks], s[1][qt]);
;         }
;       }
;       __builtin_amdgcn_s_setprio(3);
;       bf16x8 pf[QT][4];
;       const float cc = BAND ? 1.0f : scale_log2;
;       const float th = BAND ? 8.0f : 8.0f / scale_log2;
; #pragma unroll
;       for (int qt = 0; qt < QT; ++qt) {
;         if (BAND) {
; #pragma unroll
;           for (int a = 0; a < 2; ++a)
; #pragma unroll
;             for (int r = 0; r < 16; ++r) {
;               const int kidx = kt + 32 * a + (r & 7) + 8 * h + 16 * (r >> 3);
;               const int rel = kidx - (qw0 + qt * 32 + ql);
;               const bool ok = (rel >= -64) && (rel <= 64);
;               const int bi = ok ? rel + 64 : 0;
;               s[a][qt][r] = ok ? fmaf(s[a][qt][r], scale_log2, bias_l[bi]) : -1e30f;
;             }
;         }
;         float mx = s[0][qt][0];
; #pragma unroll
;         for (int r = 1; r < 16; ++r) mx = fmaxf(mx, s[0][qt][r]);
; #pragma unroll
;         for (int r = 0; r < 16; ++r) mx = fmaxf(mx, s[1][qt][r]);
;         mx = fmaxf(mx, __shfl_xor(mx, 32));
;         if (__builtin_amdgcn_ballot_w64(mx > m[qt] + th) != 0) {
;           const float mn = fmaxf(m[qt], mx);
;           const float alpha = __builtin_amdgcn_exp2f((m[qt] - mn) * cc);
;           m[qt] = mn;
;           l[qt] *= alpha;
; #pragma unroll
;           for (int r = 0; r < 16; ++r) { o[0][qt][r] *= alpha; o[1][qt][r] *= alpha; }
;         }
.Lmla_top:
	ds_read_b128 v[102:105], v235
	ds_read_b128 v[98:101], v235 offset:6656
	ds_read_b128 v[240:243], v235 offset:32
	ds_read_b128 v[244:247], v235 offset:6688
	s_waitcnt lgkmcnt(3)
	v_mfma_f32_32x32x16_bf16 v[82:97], v[102:105], v[142:145], 0
	v_mfma_f32_32x32x16_bf16 v[114:129], v[102:105], v[174:177], 0
	s_waitcnt lgkmcnt(2)
	v_mfma_f32_32x32x16_bf16 v[66:81], v[98:101], v[142:145], 0
	v_mfma_f32_32x32x16_bf16 v[98:113], v[98:101], v[174:177], 0
	s_waitcnt lgkmcnt(1)
	v_mfma_f32_32x32x16_bf16 v[82:97], v[240:243], v[150:153], v[82:97]
	v_mfma_f32_32x32x16_bf16 v[114:129], v[240:243], v[178:181], v[114:129]
	ds_read_b128 v[240:243], v235 offset:64
	s_waitcnt lgkmcnt(1)
	v_mfma_f32_32x32x16_bf16 v[66:81], v[244:247], v[150:153], v[66:81]
	v_mfma_f32_32x32x16_bf16 v[98:113], v[244:247], v[178:181], v[98:113]
	ds_read_b128 v[244:247], v235 offset:6720
	s_waitcnt lgkmcnt(1)
	v_mfma_f32_32x32x16_bf16 v[82:97], v[240:243], v[154:157], v[82:97]
	v_mfma_f32_32x32x16_bf16 v[114:129], v[240:243], v[182:185], v[114:129]
	ds_read_b128 v[240:243], v235 offset:96
	s_waitcnt lgkmcnt(1)
	v_mfma_f32_32x32x16_bf16 v[66:81], v[244:247], v[154:157], v[66:81]
	v_mfma_f32_32x32x16_bf16 v[98:113], v[244:247], v[182:185], v[98:113]
	ds_read_b128 v[244:247], v235 offset:6752
	s_waitcnt lgkmcnt(1)
	v_mfma_f32_32x32x16_bf16 v[82:97], v[240:243], v[158:161], v[82:97]
	v_mfma_f32_32x32x16_bf16 v[114:129], v[240:243], v[186:189], v[114:129]
	ds_read_b128 v[240:243], v235 offset:128
	s_waitcnt lgkmcnt(1)
	v_mfma_f32_32x32x16_bf16 v[66:81], v[244:247], v[158:161], v[66:81]
	v_mfma_f32_32x32x16_bf16 v[98:113], v[244:247], v[186:189], v[98:113]
	ds_read_b128 v[244:247], v235 offset:6784
	s_waitcnt lgkmcnt(1)
	v_mfma_f32_32x32x16_bf16 v[82:97], v[240:243], v[162:165], v[82:97]
	v_mfma_f32_32x32x16_bf16 v[114:129], v[240:243], v[190:193], v[114:129]
	ds_read_b128 v[240:243], v235 offset:160
	s_waitcnt lgkmcnt(1)
	v_mfma_f32_32x32x16_bf16 v[66:81], v[244:247], v[162:165], v[66:81]
	v_mfma_f32_32x32x16_bf16 v[98:113], v[244:247], v[190:193], v[98:113]
	ds_read_b128 v[244:247], v235 offset:6816
	s_waitcnt lgkmcnt(1)
	v_mfma_f32_32x32x16_bf16 v[82:97], v[240:243], v[166:169], v[82:97]
	v_mfma_f32_32x32x16_bf16 v[114:129], v[240:243], v[194:197], v[114:129]
	s_waitcnt lgkmcnt(0)
	v_mfma_f32_32x32x16_bf16 v[66:81], v[244:247], v[166:169], v[66:81]
	v_mfma_f32_32x32x16_bf16 v[98:113], v[244:247], v[194:197], v[98:113]
	s_cmp_lt_u32 s6, s19
	s_cbranch_scc0 .Lmla_dma_noload
	s_andn2_b32 s2, 1, s1
	s_mulk_i32 s2, 0x5800
	s_add_u32 s2, s2, s39
	s_mov_b32 m0, s2
	s_add_u32 s3, s2, 0x1000
	global_load_lds_dwordx4 v146, s[34:35]
	s_mov_b32 m0, s3
	s_add_u32 s3, s2, 0x2000
	global_load_lds_dwordx4 v147, s[34:35]
	s_mov_b32 m0, s3
	s_add_u32 s3, s2, 0x3400
	global_load_lds_dwordx4 v148, s[34:35]
	s_mov_b32 m0, s3
	s_add_u32 s3, s2, 0x4400
	global_load_lds_dwordx4 v170, s[26:27]
	s_mov_b32 m0, s3
	s_sub_u32 s3, s2, s39
	global_load_lds_dwordx4 v171, s[26:27]
	s_cmp_gt_u32 s38, 1
	s_cbranch_scc1 .Lmla_dma_x2
	s_cmp_eq_u32 s38, 0
	s_cbranch_scc0 .Lmla_dma_x1
	s_add_u32 m0, s3, 0x3000
	s_nop 0
	global_load_lds_dwordx4 v149, s[34:35]
	s_branch .Lmla_dma_x2
.Lmla_dma_x1:
	s_add_u32 m0, s3, 0x5400
	s_nop 0
	global_load_lds_dwordx4 v149, s[26:27]
.Lmla_dma_x2:
	s_add_u32 s34, s34, s84
	s_addc_u32 s35, s35, s85
	s_add_u32 s26, s26, s76
	s_addc_u32 s27, s27, s77
.Lmla_dma_noload:
	s_nop 7
	s_setprio 0
	v_max_f32_e32 v239, v82, v83
	v_max_f32_e32 v253, v114, v115
	v_max3_f32 v239, v239, v84, v85
	v_max3_f32 v253, v253, v116, v117
	v_max3_f32 v239, v239, v86, v87
	v_max3_f32 v253, v253, v118, v119
	v_max3_f32 v239, v239, v88, v89
	v_max3_f32 v253, v253, v120, v121
	v_max3_f32 v239, v239, v90, v91
	v_max3_f32 v253, v253, v122, v123
	v_max3_f32 v239, v239, v92, v93
	v_max3_f32 v253, v253, v124, v125
	v_max3_f32 v239, v239, v94, v95
	v_max3_f32 v253, v253, v126, v127
	v_max3_f32 v239, v239, v96, v97
	v_max3_f32 v253, v253, v128, v129
	v_max3_f32 v239, v239, v66, v67
	v_max3_f32 v253, v253, v98, v99
	v_max3_f32 v239, v239, v68, v69
	v_max3_f32 v253, v253, v100, v101
	v_max3_f32 v239, v239, v70, v71
	v_max3_f32 v253, v253, v102, v103
	v_max3_f32 v239, v239, v72, v73
	v_max3_f32 v253, v253, v104, v105
	v_max3_f32 v239, v239, v74, v75
	v_max3_f32 v253, v253, v106, v107
	v_max3_f32 v239, v239, v76, v77
	v_max3_f32 v253, v253, v108, v109
	v_max3_f32 v239, v239, v78, v79
	v_max3_f32 v253, v253, v110, v111
	v_max3_f32 v239, v239, v80, v81
	v_max3_f32 v253, v253, v112, v113
	v_add_f32_e32 v254, 0x4259535f, v237
	v_cmp_gt_f32_e32 vcc, v239, v254
	s_cbranch_vccz .Lmla_nr0
	ds_bpermute_b32 v254, v203, v239
	s_waitcnt lgkmcnt(0)
	v_max_f32_e32 v254, v254, v254
	v_max_f32_e32 v239, v239, v254
	v_max_f32_e32 v254, v237, v237
	v_max_f32_e32 v239, v254, v239
	v_sub_f32_e32 v237, v237, v239
	v_mul_f32_e32 v237, 0x3e16c740, v237
	v_exp_f32_e32 v254, v237
	v_mov_b32_e32 v237, v239
	v_pk_mul_f32 v[64:65], v[64:65], v[254:255] op_sel_hi:[1,0]
	v_pk_mul_f32 v[62:63], v[62:63], v[254:255] op_sel_hi:[1,0]
	v_pk_mul_f32 v[60:61], v[60:61], v[254:255] op_sel_hi:[1,0]
	v_pk_mul_f32 v[58:59], v[58:59], v[254:255] op_sel_hi:[1,0]
	v_pk_mul_f32 v[56:57], v[56:57], v[254:255] op_sel_hi:[1,0]
	v_pk_mul_f32 v[54:55], v[54:55], v[254:255] op_sel_hi:[1,0]
	v_pk_mul_f32 v[52:53], v[52:53], v[254:255] op_sel_hi:[1,0]
	v_pk_mul_f32 v[50:51], v[50:51], v[254:255] op_sel_hi:[1,0]
	v_pk_mul_f32 v[48:49], v[48:49], v[254:255] op_sel_hi:[1,0]
	v_pk_mul_f32 v[46:47], v[46:47], v[254:255] op_sel_hi:[1,0]
	v_pk_mul_f32 v[44:45], v[44:45], v[254:255] op_sel_hi:[1,0]
	v_pk_mul_f32 v[42:43], v[42:43], v[254:255] op_sel_hi:[1,0]
	v_pk_mul_f32 v[40:41], v[40:41], v[254:255] op_sel_hi:[1,0]
	v_pk_mul_f32 v[38:39], v[38:39], v[254:255] op_sel_hi:[1,0]
	v_pk_mul_f32 v[36:37], v[36:37], v[254:255] op_sel_hi:[1,0]
	v_pk_mul_f32 v[34:35], v[34:35], v[254:255] op_sel_hi:[1,0]
	v_mbcnt_lo_u32_b32 v255, -1, 0
	v_mbcnt_hi_u32_b32 v255, -1, v255
	v_add_u32_e32 v255, 16, v255
	v_lshlrev_b32_e32 v255, 2, v255
	ds_bpermute_b32 v255, v255, v254
	s_waitcnt lgkmcnt(0)
	v_mul_f32_e32 v134, v134, v254
	v_mul_f32_e32 v135, v135, v255
; DI unsigned pk2(float a, float b) { f32x2 v = {a, b}; bf16x2_t r = __builtin_convertvector(v, bf16x2_t); return __builtin_bit_cast(unsigned, r); }
; template <int DQK, bool BAND, int QT> ...
;     ...
;         if (__builtin_amdgcn_ballot_w64(mx > m[qt] + th) != 0) {
;           const float mn = fmaxf(m[qt], mx);
;           const float alpha = __builtin_amdgcn_exp2f((m[qt] - mn) * cc);
;           m[qt] = mn;
;           l[qt] *= alpha;
; #pragma unroll
;           for (int r = 0; r < 16; ++r) { o[0][qt][r] *= alpha; o[1][qt][r] *= alpha; }
;         }
;         const float mc = -m[qt] * cc;
;         float ls = 0.f;
; #pragma unroll
;         for (int a = 0; a < 2; ++a) {
; #pragma unroll
;           for (int r = 0; r < 16; ++r) { const float pv = __builtin_amdgcn_exp2f(fmaf(s[a][qt][r], cc, mc)); s[a][qt][r] = pv; ls += pv; }
; #pragma unroll
;           for (int s2 = 0; s2 < 2; ++s2) {
;             u32x4 pk;
;             pk.x = pk2(s[a][qt][8 * s2 + 0], s[a][qt][8 * s2 + 1]);
;             pk.y = pk2(s[a][qt][8 * s2 + 2], s[a][qt][8 * s2 + 3]);
;             pk.z = pk2(s[a][qt][8 * s2 + 4], s[a][qt][8 * s2 + 5]);
;             pk.w = pk2(s[a][qt][8 * s2 + 6], s[a][qt][8 * s2 + 7]);
;             pf[qt][a * 2 + s2] = __builtin_bit_cast(bf16x8, pk);
;           }
;         }
.Lmla_nr0:
	v_add_f32_e32 v254, 0x4259535f, v238
	v_cmp_gt_f32_e32 vcc, v253, v254
	s_cbranch_vccz .Lmla_nr1
	ds_bpermute_b32 v254, v203, v253
	s_waitcnt lgkmcnt(0)
	v_max_f32_e32 v254, v254, v254
	v_max_f32_e32 v253, v253, v254
	v_max_f32_e32 v254, v238, v238
	v_max_f32_e32 v253, v254, v253
	v_sub_f32_e32 v238, v238, v253
	v_mul_f32_e32 v238, 0x3e16c740, v238
	v_exp_f32_e32 v254, v238
	v_mov_b32_e32 v238, v253
	v_pk_mul_f32 v[32:33], v[32:33], v[254:255] op_sel_hi:[1,0]
	v_pk_mul_f32 v[30:31], v[30:31], v[254:255] op_sel_hi:[1,0]
	v_pk_mul_f32 v[28:29], v[28:29], v[254:255] op_sel_hi:[1,0]
	v_pk_mul_f32 v[26:27], v[26:27], v[254:255] op_sel_hi:[1,0]
	v_pk_mul_f32 v[24:25], v[24:25], v[254:255] op_sel_hi:[1,0]
	v_pk_mul_f32 v[22:23], v[22:23], v[254:255] op_sel_hi:[1,0]
	v_pk_mul_f32 v[20:21], v[20:21], v[254:255] op_sel_hi:[1,0]
	v_pk_mul_f32 v[18:19], v[18:19], v[254:255] op_sel_hi:[1,0]
	v_pk_mul_f32 v[16:17], v[16:17], v[254:255] op_sel_hi:[1,0]
	v_pk_mul_f32 v[14:15], v[14:15], v[254:255] op_sel_hi:[1,0]
	v_pk_mul_f32 v[12:13], v[12:13], v[254:255] op_sel_hi:[1,0]
	v_pk_mul_f32 v[10:11], v[10:11], v[254:255] op_sel_hi:[1,0]
	v_pk_mul_f32 v[8:9], v[8:9], v[254:255] op_sel_hi:[1,0]
	v_pk_mul_f32 v[6:7], v[6:7], v[254:255] op_sel_hi:[1,0]
	v_pk_mul_f32 v[4:5], v[4:5], v[254:255] op_sel_hi:[1,0]
	v_pk_mul_f32 v[2:3], v[2:3], v[254:255] op_sel_hi:[1,0]
	v_mbcnt_lo_u32_b32 v255, -1, 0
	v_mbcnt_hi_u32_b32 v255, -1, v255
	v_add_u32_e32 v255, 16, v255
	v_lshlrev_b32_e32 v255, 2, v255
	ds_bpermute_b32 v255, v255, v254
	s_waitcnt lgkmcnt(0)
	v_mul_f32_e32 v138, v138, v254
	v_mul_f32_e32 v139, v139, v255
.Lmla_nr1:
	v_mul_f32_e32 v254, 0xbe16c740, v237
	v_mul_f32_e32 v255, 0xbe16c740, v238
	v_fmamk_f32 v82, v82, 0x3e16c740, v254
	v_fmamk_f32 v114, v114, 0x3e16c740, v255
	v_fmamk_f32 v83, v83, 0x3e16c740, v254
	v_fmamk_f32 v115, v115, 0x3e16c740, v255
	v_fmamk_f32 v84, v84, 0x3e16c740, v254
	v_fmamk_f32 v116, v116, 0x3e16c740, v255
	v_fmamk_f32 v85, v85, 0x3e16c740, v254
	v_fmamk_f32 v117, v117, 0x3e16c740, v255
	v_fmamk_f32 v86, v86, 0x3e16c740, v254
	v_fmamk_f32 v118, v118, 0x3e16c740, v255
	v_fmamk_f32 v87, v87, 0x3e16c740, v254
	v_fmamk_f32 v119, v119, 0x3e16c740, v255
	v_fmamk_f32 v88, v88, 0x3e16c740, v254
	v_fmamk_f32 v120, v120, 0x3e16c740, v255
	v_fmamk_f32 v89, v89, 0x3e16c740, v254
	v_fmamk_f32 v121, v121, 0x3e16c740, v255
	v_exp_f32_e32 v82, v82
	v_exp_f32_e32 v114, v114
	v_exp_f32_e32 v83, v83
	v_exp_f32_e32 v115, v115
	v_exp_f32_e32 v84, v84
	v_exp_f32_e32 v116, v116
	v_exp_f32_e32 v85, v85
	v_exp_f32_e32 v117, v117
	v_exp_f32_e32 v86, v86
	v_exp_f32_e32 v118, v118
	v_exp_f32_e32 v87, v87
	v_exp_f32_e32 v119, v119
	v_exp_f32_e32 v88, v88
	v_exp_f32_e32 v120, v120
	v_exp_f32_e32 v89, v89
	v_exp_f32_e32 v121, v121
	v_fmamk_f32 v90, v90, 0x3e16c740, v254
	v_fmamk_f32 v122, v122, 0x3e16c740, v255
	v_fmamk_f32 v91, v91, 0x3e16c740, v254
	v_fmamk_f32 v123, v123, 0x3e16c740, v255
	v_fmamk_f32 v92, v92, 0x3e16c740, v254
	v_fmamk_f32 v124, v124, 0x3e16c740, v255
	v_fmamk_f32 v93, v93, 0x3e16c740, v254
	v_fmamk_f32 v125, v125, 0x3e16c740, v255
	v_fmamk_f32 v94, v94, 0x3e16c740, v254
	v_fmamk_f32 v126, v126, 0x3e16c740, v255
	v_fmamk_f32 v95, v95, 0x3e16c740, v254
	v_fmamk_f32 v127, v127, 0x3e16c740, v255
	v_fmamk_f32 v96, v96, 0x3e16c740, v254
	v_fmamk_f32 v128, v128, 0x3e16c740, v255
	v_fmamk_f32 v97, v97, 0x3e16c740, v254
	v_fmamk_f32 v129, v129, 0x3e16c740, v255
	v_exp_f32_e32 v90, v90
	v_exp_f32_e32 v122, v122
	v_exp_f32_e32 v91, v91
	v_exp_f32_e32 v123, v123
	v_exp_f32_e32 v92, v92
	v_exp_f32_e32 v124, v124
	v_exp_f32_e32 v93, v93
	v_exp_f32_e32 v125, v125
	v_exp_f32_e32 v94, v94
	v_exp_f32_e32 v126, v126
	v_exp_f32_e32 v95, v95
	v_exp_f32_e32 v127, v127
	v_exp_f32_e32 v96, v96
	v_exp_f32_e32 v128, v128
	v_exp_f32_e32 v97, v97
	v_exp_f32_e32 v129, v129
	v_cvt_pk_bf16_f32 v82, v82, v83
	v_cvt_pk_bf16_f32 v114, v114, v115
	v_cvt_pk_bf16_f32 v83, v84, v85
	v_cvt_pk_bf16_f32 v115, v116, v117
	v_cvt_pk_bf16_f32 v84, v86, v87
	v_cvt_pk_bf16_f32 v116, v118, v119
	v_cvt_pk_bf16_f32 v85, v88, v89
	v_cvt_pk_bf16_f32 v117, v120, v121
	v_fmamk_f32 v66, v66, 0x3e16c740, v254
	v_fmamk_f32 v98, v98, 0x3e16c740, v255
	v_fmamk_f32 v67, v67, 0x3e16c740, v254
	v_fmamk_f32 v99, v99, 0x3e16c740, v255
	v_fmamk_f32 v68, v68, 0x3e16c740, v254
	v_fmamk_f32 v100, v100, 0x3e16c740, v255
	v_fmamk_f32 v69, v69, 0x3e16c740, v254
	v_fmamk_f32 v101, v101, 0x3e16c740, v255
	v_fmamk_f32 v70, v70, 0x3e16c740, v254
	v_fmamk_f32 v102, v102, 0x3e16c740, v255
	v_fmamk_f32 v71, v71, 0x3e16c740, v254
	v_fmamk_f32 v103, v103, 0x3e16c740, v255
	v_fmamk_f32 v72, v72, 0x3e16c740, v254
	v_fmamk_f32 v104, v104, 0x3e16c740, v255
	v_fmamk_f32 v73, v73, 0x3e16c740, v254
	v_fmamk_f32 v105, v105, 0x3e16c740, v255
	v_exp_f32_e32 v66, v66
	v_exp_f32_e32 v98, v98
	v_exp_f32_e32 v67, v67
	v_exp_f32_e32 v99, v99
	v_exp_f32_e32 v68, v68
	v_exp_f32_e32 v100, v100
	v_exp_f32_e32 v69, v69
	v_exp_f32_e32 v101, v101
	v_exp_f32_e32 v70, v70
	v_exp_f32_e32 v102, v102
	v_exp_f32_e32 v71, v71
	v_exp_f32_e32 v103, v103
; #define MFMA(a, b, c) __builtin_amdgcn_mfma_f32_32x32x16_bf16((a), (b), (c), 0, 0, 0)
; DI unsigned pk2(float a, float b) { f32x2 v = {a, b}; bf16x2_t r = __builtin_convertvector(v, bf16x2_t); return __builtin_bit_cast(unsigned, r); }
; template <int DQK, bool BAND, int QT> ...
;     ...
;         const float mc = -m[qt] * cc;
;         float ls = 0.f;
; #pragma unroll
;         for (int a = 0; a < 2; ++a) {
; #pragma unroll
;           for (int r = 0; r < 16; ++r) { const float pv = __builtin_amdgcn_exp2f(fmaf(s[a][qt][r], cc, mc)); s[a][qt][r] = pv; ls += pv; }
; #pragma unroll
;           for (int s2 = 0; s2 < 2; ++s2) {
;             u32x4 pk;
;             pk.x = pk2(s[a][qt][8 * s2 + 0], s[a][qt][8 * s2 + 1]);
;             pk.y = pk2(s[a][qt][8 * s2 + 2], s[a][qt][8 * s2 + 3]);
;             pk.z = pk2(s[a][qt][8 * s2 + 4], s[a][qt][8 * s2 + 5]);
;             pk.w = pk2(s[a][qt][8 * s2 + 6], s[a][qt][8 * s2 + 7]);
;             pf[qt][a * 2 + s2] = __builtin_bit_cast(bf16x8, pk);
;           }
;         }
;         l[qt] += ls;
;       }
;       __builtin_amdgcn_s_setprio(0);
;       if (more) lstore(lds + ((it + 1) & 1) * ST);
; #pragma unroll
;       for (int ks = 0; ks < 4; ++ks) {
;         const bf16x8 v0 = *(const bf16x8*)(st + v_rd + ks * 32);
;         const bf16x8 v1 = *(const bf16x8*)(st + v_rd + 32 * LROW + ks * 32);
; #pragma unroll
;         for (int qt = 0; qt < QT; ++qt) {
;           o[0][qt] = MFMA(v0, pf[qt][ks], o[0][qt]);
;           o[1][qt] = MFMA(v1, pf[qt][ks], o[1][qt]);
;         }
;       }
;     } else {
;       if (more) lstore(lds + ((it + 1) & 1) * ST);
;     }
;     __syncthreads();
;   }
; #pragma unroll
;   for (int qt = 0; qt < QT; ++qt) {
;     const float lt = l[qt] + __shfl_xor(l[qt], 32);
;     const float inv = __builtin_amdgcn_rcpf(lt);
	v_exp_f32_e32 v72, v72
	v_exp_f32_e32 v104, v104
	v_exp_f32_e32 v73, v73
	v_exp_f32_e32 v105, v105
	v_cvt_pk_bf16_f32 v90, v90, v91
	v_cvt_pk_bf16_f32 v122, v122, v123
	v_cvt_pk_bf16_f32 v91, v92, v93
	v_cvt_pk_bf16_f32 v123, v124, v125
	v_cvt_pk_bf16_f32 v92, v94, v95
	v_cvt_pk_bf16_f32 v124, v126, v127
	v_cvt_pk_bf16_f32 v93, v96, v97
	v_cvt_pk_bf16_f32 v125, v128, v129
	v_fmamk_f32 v74, v74, 0x3e16c740, v254
	v_fmamk_f32 v106, v106, 0x3e16c740, v255
	v_fmamk_f32 v75, v75, 0x3e16c740, v254
	v_fmamk_f32 v107, v107, 0x3e16c740, v255
	v_fmamk_f32 v76, v76, 0x3e16c740, v254
	v_fmamk_f32 v108, v108, 0x3e16c740, v255
	v_fmamk_f32 v77, v77, 0x3e16c740, v254
	v_fmamk_f32 v109, v109, 0x3e16c740, v255
	v_fmamk_f32 v78, v78, 0x3e16c740, v254
	v_fmamk_f32 v110, v110, 0x3e16c740, v255
	v_fmamk_f32 v79, v79, 0x3e16c740, v254
	v_fmamk_f32 v111, v111, 0x3e16c740, v255
	v_fmamk_f32 v80, v80, 0x3e16c740, v254
	v_fmamk_f32 v112, v112, 0x3e16c740, v255
	v_fmamk_f32 v81, v81, 0x3e16c740, v254
	v_fmamk_f32 v113, v113, 0x3e16c740, v255
	v_exp_f32_e32 v74, v74
	v_exp_f32_e32 v106, v106
	v_exp_f32_e32 v75, v75
	v_exp_f32_e32 v107, v107
	v_exp_f32_e32 v76, v76
	v_exp_f32_e32 v108, v108
	v_exp_f32_e32 v77, v77
	v_exp_f32_e32 v109, v109
	v_exp_f32_e32 v78, v78
	v_exp_f32_e32 v110, v110
	v_exp_f32_e32 v79, v79
	v_exp_f32_e32 v111, v111
	v_exp_f32_e32 v80, v80
	v_exp_f32_e32 v112, v112
	v_exp_f32_e32 v81, v81
	v_exp_f32_e32 v113, v113
	v_cvt_pk_bf16_f32 v66, v66, v67
	v_cvt_pk_bf16_f32 v98, v98, v99
	v_cvt_pk_bf16_f32 v67, v68, v69
	v_cvt_pk_bf16_f32 v99, v100, v101
	v_cvt_pk_bf16_f32 v68, v70, v71
	v_cvt_pk_bf16_f32 v100, v102, v103
	v_cvt_pk_bf16_f32 v69, v72, v73
	v_cvt_pk_bf16_f32 v101, v104, v105
	v_cvt_pk_bf16_f32 v74, v74, v75
	v_cvt_pk_bf16_f32 v106, v106, v107
	v_cvt_pk_bf16_f32 v75, v76, v77
	v_cvt_pk_bf16_f32 v107, v108, v109
	v_cvt_pk_bf16_f32 v76, v78, v79
	v_cvt_pk_bf16_f32 v108, v110, v111
	v_cvt_pk_bf16_f32 v77, v80, v81
	v_cvt_pk_bf16_f32 v109, v112, v113
	s_setprio 2
	ds_read_b128 v[86:89], v234 offset:13312
	ds_read_b128 v[94:97], v234 offset:17920
	ds_read_b128 v[70:73], v234 offset:13344
	ds_read_b128 v[78:81], v234 offset:17952
	ds_read_b128 v[118:121], v234 offset:13376
	ds_read_b128 v[126:129], v234 offset:17984
	ds_read_b128 v[102:105], v234 offset:13408
	ds_read_b128 v[110:113], v234 offset:18016
	s_waitcnt lgkmcnt(7)
	v_mfma_f32_32x32x16_bf16 v[50:65], v[86:89], v[82:85], v[50:65]
	v_mfma_f32_32x32x16_bf16 v[18:33], v[86:89], v[114:117], v[18:33]
	s_waitcnt lgkmcnt(6)
	v_mfma_f32_32x32x16_bf16 v[34:49], v[94:97], v[82:85], v[34:49]
	v_mfma_f32_32x32x16_bf16 v[2:17], v[94:97], v[114:117], v[2:17]
	v_mfma_f32_16x16x32_bf16 v[134:137], v[130:133], v[82:85], v[134:137]
	v_mfma_f32_16x16x32_bf16 v[138:141], v[130:133], v[114:117], v[138:141]
	s_waitcnt lgkmcnt(5)
	v_mfma_f32_32x32x16_bf16 v[50:65], v[70:73], v[90:93], v[50:65]
	v_mfma_f32_32x32x16_bf16 v[18:33], v[70:73], v[122:125], v[18:33]
	s_waitcnt lgkmcnt(4)
	v_mfma_f32_32x32x16_bf16 v[34:49], v[78:81], v[90:93], v[34:49]
	v_mfma_f32_32x32x16_bf16 v[2:17], v[78:81], v[122:125], v[2:17]
	v_mfma_f32_16x16x32_bf16 v[134:137], v[130:133], v[90:93], v[134:137]
	v_mfma_f32_16x16x32_bf16 v[138:141], v[130:133], v[122:125], v[138:141]
	s_waitcnt lgkmcnt(3)
	v_mfma_f32_32x32x16_bf16 v[50:65], v[118:121], v[66:69], v[50:65]
	v_mfma_f32_32x32x16_bf16 v[18:33], v[118:121], v[98:101], v[18:33]
	s_waitcnt lgkmcnt(2)
	v_mfma_f32_32x32x16_bf16 v[34:49], v[126:129], v[66:69], v[34:49]
	v_mfma_f32_32x32x16_bf16 v[2:17], v[126:129], v[98:101], v[2:17]
	v_mfma_f32_16x16x32_bf16 v[134:137], v[130:133], v[66:69], v[134:137]
	v_mfma_f32_16x16x32_bf16 v[138:141], v[130:133], v[98:101], v[138:141]
	s_bitcmp1_b32 s1, 0
	s_cselect_b32 s7, -1, 1
	s_mulk_i32 s7, 0x5800
	v_add_u32_e32 v235, s7, v235
	v_add_u32_e32 v234, s7, v234
	s_add_i32 s1, s1, 1
	s_add_i32 s6, s6, 64
	s_waitcnt vmcnt(0) lgkmcnt(0)
	s_barrier
	v_mfma_f32_32x32x16_bf16 v[50:65], v[102:105], v[74:77], v[50:65]
	v_mfma_f32_32x32x16_bf16 v[18:33], v[102:105], v[106:109], v[18:33]
	v_mfma_f32_32x32x16_bf16 v[34:49], v[110:113], v[74:77], v[34:49]
	v_mfma_f32_32x32x16_bf16 v[2:17], v[110:113], v[106:109], v[2:17]
	v_mfma_f32_16x16x32_bf16 v[134:137], v[130:133], v[74:77], v[134:137]
	v_mfma_f32_16x16x32_bf16 v[138:141], v[130:133], v[106:109], v[138:141]
	s_cmp_lg_u32 s21, s1
	s_cbranch_scc1 .Lmla_top
	s_setprio 0
	s_nop 7
	v_mbcnt_lo_u32_b32 v254, -1, 0
	v_mbcnt_hi_u32_b32 v254, -1, v254
	v_and_b32_e32 v255, 15, v254
	v_lshlrev_b32_e32 v255, 2, v255
	ds_bpermute_b32 v239, v255, v134
	ds_bpermute_b32 v253, v255, v135
	s_waitcnt lgkmcnt(0)
	v_cmp_gt_u32_e32 vcc, 16, v254
	s_nop 1
	v_cndmask_b32_e32 v236, v253, v239, vcc
	v_cmp_gt_u32_e32 vcc, 32, v254
	s_nop 1
	v_cndmask_b32_e32 v236, 0, v236, vcc
	ds_bpermute_b32 v239, v255, v138
	ds_bpermute_b32 v253, v255, v139
	s_waitcnt lgkmcnt(0)
	v_cmp_gt_u32_e32 vcc, 16, v254
	s_nop 1
	v_cndmask_b32_e32 v207, v253, v239, vcc
	v_cmp_gt_u32_e32 vcc, 32, v254
	s_nop 1
	v_cndmask_b32_e32 v207, 0, v207, vcc
	s_branch .LBB0_663
	s_nop 0
